# v11 plus FoX unit prologue de-serialised: key-norm load and wave-0 c-row loads no longer waited at issue
# baseline (speedup 1.0000x reference)
; template <int MODE> ...
;     ...
;     for (;;) {
;         int idx;
;         if (counter) {
;             if (threadIdx.x == 0) *slot = (int)__hip_atomic_fetch_add(counter, 1u, __ATOMIC_RELAXED, __HIP_MEMORY_SCOPE_AGENT);
;             __syncthreads(); idx = *slot - idx0; __syncthreads();
;             if (idx >= nunits) break;
;             if (idx < 0) continue;
;         } else { idx = (int)blockIdx.x; if (idx >= nunits) break; }
;         const int h = head_major ? (nheads - 1 - idx / 64) : (idx % nheads), qb = head_major ? (63 - idx % 64) : (63 - idx / nheads), hh = head0 + h;
;         att::AttnArgs a; a.Q = Q + hh * 64; a.ldq = ldq; a.K = K + hh * 64; a.V = V + hh * 64; a.ldkv = ldkv; a.O = O + hh * 64; a.ldo = ldo;
;         a.cf = cf ? cf + (size_t)hh * S : nullptr; a.kmax2 = kmx ? (__uint_as_float(kmx[2 * hh]) + __uint_as_float(kmx[2 * hh + 1])) * 1.02f : 0.f;
.LBB0_950:
	s_or_b64 exec, exec, s[4:5]
	v_mov_b32_e32 v0, s95
	s_waitcnt lgkmcnt(0)
	s_barrier
	ds_read_b32 v0, v0
	s_movk_i32 s1, 0x3ff
	s_mov_b64 s[4:5], -1
	s_waitcnt lgkmcnt(0)
	s_barrier
	v_cmp_lt_i32_e32 vcc, s1, v0
	v_readfirstlane_b32 s0, v0
	s_cbranch_vccnz .LBB0_945
	s_cmp_lt_i32 s0, 0
	s_cbranch_scc1 .LBB0_944
	s_lshr_b32 s1, s0, 6
	s_sub_i32 s1, 15, s1
	v_mov_b32_e32 v157, 0
	s_andn2_b64 vcc, exec, s[18:19]
	v_mov_b32_e32 v9, 0
	v_mov_b32_e32 v230, 0
	v_mov_b32_e32 v231, 0
	s_cbranch_vccnz .LBB0_954
	s_lshl_b32 s80, s1, 1
	s_lshl_b64 s[2:3], s[80:81], 2
	s_add_u32 s2, s38, s2
	s_addc_u32 s3, s39, s3
	global_load_dwordx2 v[230:231], v1, s[2:3]

; #define LAS __attribute__((address_space(3)))
; template <int MODE>
; __device__ __forceinline__ void attn_unit(LAS unsigned char* lds, const AttnArgs& A, int qb) {
;     int tid_ = threadIdx.x; asm volatile("" : "+v"(tid_)); const int tid = tid_, lane = tid & 63, wid = __builtin_amdgcn_readfirstlane(tid >> 6), r32 = lane & 31, hi = lane >> 5;
;     const int q0 = qb * 256, w0 = q0 + wid * 32, row = w0 + r32;
;     bf16x8 qr[4];
; #pragma unroll
;     for (int d0 = 0; d0 < 4; ++d0) qr[d0] = *(const bf16x8*)(A.Q + (size_t)row * A.ldq + d0 * 16 + hi * 8);
;     int i1 = -1, i2 = -1, i3 = -1; unsigned long long wmask = 0ull;
;     if (MODE == M_MOBA) {
;         const int own = qb;
;         LAS float* km = (LAS float*)(lds + KM_OFF);
;         {
;             float kp_[8][4];
; #pragma unroll
;             for (int k = 0; k < 8; ++k) { const int idx = tid + 512 * k; const bool ok = idx < own * 64; const float* p = A.kpart + (size_t)((ok ? idx : 0) >> 6) * 256 + (idx & 63);
;                 kp_[k][0] = p[0]; kp_[k][1] = p[64]; kp_[k][2] = p[128]; kp_[k][3] = p[192]; }
; #pragma unroll
;             for (int k = 0; k < 8; ++k) { const int idx = tid + 512 * k; if (idx < own * 64) km[idx] = ((kp_[k][0] + kp_[k][1]) + (kp_[k][2] + kp_[k][3])) * (1.0f / 256.0f); }
;         }
;         __syncthreads();
;         float qf[32];
; #pragma unroll
;         for (int d0 = 0; d0 < 4; ++d0)
; #pragma unroll
;             for (int e = 0; e < 8; ++e) qf[d0 * 8 + e] = bf2f(qr[d0][e]);
;         float v1 = -INFINITY, v2 = -INFINITY, v3 = -INFINITY;
; #pragma unroll 4
;         for (int j = 0; j < own; ++j) {
;             float g = 0.f;
; #pragma unroll
;             for (int d0 = 0; d0 < 4; ++d0) { const f32x4 a = *(const LAS f32x4*)(km + j * 64 + d0 * 16 + hi * 8), b = *(const LAS f32x4*)(km + j * 64 + d0 * 16 + hi * 8 + 4);
;                 g += (qf[d0 * 8 + 0] * a[0] + qf[d0 * 8 + 1] * a[1]) + (qf[d0 * 8 + 2] * a[2] + qf[d0 * 8 + 3] * a[3]) + (qf[d0 * 8 + 4] * b[0] + qf[d0 * 8 + 5] * b[1]) + (qf[d0 * 8 + 6] * b[2] + qf[d0 * 8 + 7] * b[3]); }
;             const float go = __shfl_xor(g, 32); g = hi ? (go + g) : (g + go);
;             if (g > v1) { v3 = v2; i3 = i2; v2 = v1; i2 = i1; v1 = g; i1 = j; } else if (g > v2) { v3 = v2; i3 = i2; v2 = g; i2 = j; } else if (g > v3) { v3 = g; i3 = j; }
;         }
.Lfox_prio_skip:
	s_lshl_b32 s80, s0, 8
	s_lshl_b32 s43, s42, 5
	v_and_b32_e32 v8, 31, v2
	s_add_i32 s43, s43, s80
	v_or_b32_e32 v154, s43, v8
	v_ashrrev_i32_e32 v155, 31, v154
	v_bfe_u32 v7, v2, 5, 1
	v_lshlrev_b64 v[4:5], 11, v[154:155]
	v_lshl_add_u64 v[4:5], s[2:3], 0, v[4:5]
	v_lshlrev_b32_e32 v0, 4, v7
	v_lshl_add_u64 v[4:5], v[4:5], 0, v[0:1]
	global_load_dwordx4 v[98:101], v[4:5], off
	global_load_dwordx4 v[102:105], v[4:5], off offset:32
	global_load_dwordx4 v[106:109], v[4:5], off offset:64
	global_load_dwordx4 v[110:113], v[4:5], off offset:96
	v_and_b32_e32 v6, 63, v2
	s_lshl_b32 s2, s42, 3
	s_ashr_i32 s3, s2, 31
	s_lshl_b64 s[10:11], s[2:3], 1
	v_cmp_gt_i32_e64 s[6:7], 64, v2
	s_waitcnt vmcnt(3)
	v_add_f32_e32 v230, v230, v231
	v_mul_f32_e32 v9, 0x3f828f5c, v230
	v_and_b32_e32 v4, 0xffff0000, v98
	v_lshlrev_b32_e32 v3, 16, v98
	v_mul_f32_e32 v10, v4, v4
	v_fmac_f32_e32 v10, v3, v3
	v_lshlrev_b32_e32 v3, 16, v99
	v_fmac_f32_e32 v10, v3, v3
	v_and_b32_e32 v3, 0xffff0000, v99
	v_fmac_f32_e32 v10, v3, v3
	v_lshlrev_b32_e32 v3, 16, v100
	v_fmac_f32_e32 v10, v3, v3
	v_and_b32_e32 v3, 0xffff0000, v100
	v_fmac_f32_e32 v10, v3, v3
	v_lshlrev_b32_e32 v3, 16, v101
	v_fmac_f32_e32 v10, v3, v3
	v_and_b32_e32 v3, 0xffff0000, v101
	v_fmac_f32_e32 v10, v3, v3
	s_waitcnt vmcnt(2)
	v_lshlrev_b32_e32 v3, 16, v102
	v_fmac_f32_e32 v10, v3, v3
	v_and_b32_e32 v3, 0xffff0000, v102
	v_fmac_f32_e32 v10, v3, v3
	v_lshlrev_b32_e32 v3, 16, v103
	v_fmac_f32_e32 v10, v3, v3
	v_and_b32_e32 v3, 0xffff0000, v103
	v_fmac_f32_e32 v10, v3, v3
	v_lshlrev_b32_e32 v3, 16, v104
	v_fmac_f32_e32 v10, v3, v3
	v_and_b32_e32 v3, 0xffff0000, v104
	v_fmac_f32_e32 v10, v3, v3
	v_lshlrev_b32_e32 v3, 16, v105
	v_fmac_f32_e32 v10, v3, v3
	v_and_b32_e32 v3, 0xffff0000, v105
	v_fmac_f32_e32 v10, v3, v3
	s_waitcnt vmcnt(1)
	v_lshlrev_b32_e32 v3, 16, v106
	v_fmac_f32_e32 v10, v3, v3
	v_and_b32_e32 v3, 0xffff0000, v106
	v_fmac_f32_e32 v10, v3, v3
	v_lshlrev_b32_e32 v3, 16, v107
	v_fmac_f32_e32 v10, v3, v3
	v_and_b32_e32 v3, 0xffff0000, v107
	v_fmac_f32_e32 v10, v3, v3
	v_lshlrev_b32_e32 v3, 16, v108
	v_fmac_f32_e32 v10, v3, v3
	v_and_b32_e32 v3, 0xffff0000, v108
	v_fmac_f32_e32 v10, v3, v3
	v_lshlrev_b32_e32 v3, 16, v109
	v_fmac_f32_e32 v10, v3, v3
	v_and_b32_e32 v3, 0xffff0000, v109
	v_fmac_f32_e32 v10, v3, v3
	s_waitcnt vmcnt(0)
	v_lshlrev_b32_e32 v3, 16, v110
	v_fmac_f32_e32 v10, v3, v3
	v_and_b32_e32 v3, 0xffff0000, v110
	v_fmac_f32_e32 v10, v3, v3
	v_lshlrev_b32_e32 v3, 16, v111
	v_fmac_f32_e32 v10, v3, v3
	v_and_b32_e32 v3, 0xffff0000, v111
	v_fmac_f32_e32 v10, v3, v3
	v_lshlrev_b32_e32 v3, 16, v112
	v_fmac_f32_e32 v10, v3, v3
	v_and_b32_e32 v3, 0xffff0000, v112
	v_fmac_f32_e32 v10, v3, v3
	v_lshlrev_b32_e32 v3, 16, v113
	v_fmac_f32_e32 v10, v3, v3
	v_and_b32_e32 v3, 0xffff0000, v113
	v_and_b32_e32 v4, 64, v223
	v_fmac_f32_e32 v10, v3, v3
	v_xor_b32_e32 v3, 32, v223
	v_add_u32_e32 v4, 64, v4
	v_cmp_lt_i32_e32 vcc, v3, v4
	v_lshl_add_u64 v[4:5], v[154:155], 2, s[22:23]
	global_load_dword v11, v[4:5], off
	v_cndmask_b32_e32 v3, v223, v3, vcc
	v_lshlrev_b32_e32 v176, 2, v3
	v_or_b32_e32 v3, s80, v6
	v_mov_b32_e32 v4, 0x60000
	v_lshl_or_b32 v4, v3, 11, v4
	v_mov_b32_e32 v5, v1
	v_lshl_add_u64 v[14:15], s[4:5], 0, v[4:5]
	v_lshl_add_u64 v[4:5], s[8:9], 0, v[4:5]
	v_lshl_add_u64 v[14:15], v[14:15], 0, s[10:11]
	v_lshl_add_u64 v[4:5], v[4:5], 0, s[10:11]
	global_load_dwordx4 v[114:117], v[14:15], off
	global_load_dwordx4 v[118:121], v[4:5], off
	ds_bpermute_b32 v12, v176, v10
	v_ashrrev_i32_e32 v3, 31, v2
	s_and_saveexec_b64 s[24:25], s[6:7]
	s_cbranch_execz .LBB0_956
	v_lshl_add_u64 v[4:5], v[2:3], 0, s[80:81]
	v_lshl_add_u64 v[4:5], v[4:5], 2, s[22:23]
	global_load_dword v157, v[4:5], off offset:768
.LBB0_956:
	s_or_b64 exec, exec, s[24:25]
	v_add_u32_e32 v4, s80, v6
	v_mov_b32_e32 v5, 0x40000
	v_lshl_add_u32 v14, v4, 11, v5
	v_mov_b32_e32 v15, v1
	v_lshl_add_u64 v[16:17], s[4:5], 0, v[14:15]
	v_lshl_add_u64 v[14:15], s[8:9], 0, v[14:15]
	v_lshl_add_u64 v[16:17], v[16:17], 0, s[10:11]
	v_lshl_add_u64 v[14:15], v[14:15], 0, s[10:11]
	global_load_dwordx4 v[122:125], v[16:17], off
	global_load_dwordx4 v[126:129], v[14:15], off
	v_mov_b32_e32 v178, 0
	v_mov_b32_e32 v177, 0
	s_and_saveexec_b64 s[24:25], s[6:7]
	s_cbranch_execz .LBB0_958
	v_lshl_add_u64 v[14:15], v[2:3], 0, s[80:81]
	v_lshl_add_u64 v[14:15], v[14:15], 2, s[22:23]
	global_load_dword v177, v[14:15], off offset:512
.LBB0_958:
	s_or_b64 exec, exec, s[24:25]
	v_lshl_add_u32 v4, v4, 11, v224
	v_mov_b32_e32 v5, v1
	v_lshl_add_u64 v[14:15], s[4:5], 0, v[4:5]
	v_lshl_add_u64 v[4:5], s[8:9], 0, v[4:5]
	v_lshl_add_u64 v[14:15], v[14:15], 0, s[10:11]
	v_lshl_add_u64 v[4:5], v[4:5], 0, s[10:11]
	global_load_dwordx4 v[130:133], v[14:15], off
	global_load_dwordx4 v[134:137], v[4:5], off
	s_and_saveexec_b64 s[4:5], s[6:7]
	s_cbranch_execz .LBB0_960
	v_lshl_add_u64 v[4:5], v[2:3], 0, s[80:81]
	v_lshl_add_u64 v[4:5], v[4:5], 2, s[22:23]
	global_load_dword v178, v[4:5], off offset:256
; __device__ __forceinline__ float bf2f(short s) { return __uint_as_float(((unsigned)(unsigned short)s) << 16); }
; #define LOADT(i, kreg, vreg, creg) do { const int k0_ = KEY0(i); kreg = *(const u32x4*)(A.K + (size_t)(k0_ + lane) * A.ldkv + wid * 8); vreg = *(const u32x4*)(A.V + (size_t)(k0_ + lane) * A.ldkv + wid * 8); \
;         if (MODE == M_FOX) { if (tid < 64) creg = A.cf[k0_ + tid] * LOG2E; } } while (0)
; template <int MODE>
; __device__ __forceinline__ void attn_unit(LAS unsigned char* lds, const AttnArgs& A, int qb) {
;     ...
;     float qb2 = 0.f, cq2 = 0.f;
;     if (MODE == M_FOX) {
;         float s = 0.f;
; #pragma unroll
;         for (int d0 = 0; d0 < 4; ++d0)
; #pragma unroll
;             for (int e = 0; e < 8; ++e) { const float x = bf2f(qr[d0][e]); s += x * x; }
;         s += __shfl_xor(s, 32);
;         qb2 = sqrtf(s * A.kmax2) * C2 * 1.01f;
;         cq2 = A.cf[row] * LOG2E;
;     }
;     const int NT = (MODE == M_XA || MODE == M_MOBA) ? 4 : (q0 / 64 + 4);
;     f32x16 o0, o1;
; #pragma unroll
;     for (int r = 0; r < 16; ++r) { o0[r] = 0.f; o1[r] = 0.f; }
;     float m_run = -1e30f, l_run = 0.f, T = 0.f;
;     u32x4 k1 = (u32x4){0u, 0u, 0u, 0u}, v1 = k1, k2 = k1, v2 = k1, k3 = k1, v3 = k1; float c1 = 0.f, c2 = 0.f, c3 = 0.f;
;     ...
;     LOADT(0, k1, v1, c1); if (NT > 1) LOADT(1, k2, v2, c2); if (NT > 2) LOADT(2, k3, v3, c3);
;     STORET(0, k1, v1, c1);
;     __syncthreads();
.LBB0_960:
	s_or_b64 exec, exec, s[4:5]
	s_lshl_b32 s2, s42, 10
	s_add_i32 s46, s2, 0
	v_lshlrev_b32_e32 v179, 4, v6
	s_lshl_b32 s3, s42, 7
	v_add_u32_e32 v180, s46, v179
	s_add_i32 s46, s46, s3
	v_lshlrev_b32_e32 v181, 1, v6
	v_add_u32_e32 v182, s46, v181
	v_lshl_add_u32 v183, v2, 2, 0
	s_waitcnt vmcnt(5)
	ds_write_b128 v180, v[114:117]
	s_waitcnt vmcnt(4)
	ds_write_b16 v182, v118 offset:8192
	ds_write_b16_d16_hi v182, v118 offset:8336
	ds_write_b16 v182, v119 offset:8480
	ds_write_b16_d16_hi v182, v119 offset:8624
	ds_write_b16 v182, v120 offset:8768
	ds_write_b16_d16_hi v182, v120 offset:8912
	ds_write_b16 v182, v121 offset:9056
	ds_write_b16_d16_hi v182, v121 offset:9200
	s_and_saveexec_b64 s[4:5], s[6:7]
	v_mul_f32_e32 v157, 0x3fb8aa3b, v157
	ds_write_b32 v183, v157 offset:17408
	s_or_b64 exec, exec, s[4:5]
	s_waitcnt lgkmcnt(9)
	v_add_f32_e32 v4, v10, v12
	v_mul_f32_e32 v4, v9, v4
	s_mov_b32 s2, 0xf800000
	v_mul_f32_e32 v5, 0x4f800000, v4
	v_cmp_gt_f32_e32 vcc, s2, v4
	s_mul_i32 s4, s42, 0xfffffb84
	s_add_i32 s46, s46, s4
	v_cndmask_b32_e32 v4, v4, v5, vcc
	v_sqrt_f32_e32 v5, v4
	s_mov_b32 s4, 0x3fb8aa3b
	v_mul_f32_e32 v184, 0x3fb8aa3b, v11
	s_lshl_b32 s44, s0, 2
	v_add_u32_e32 v9, -1, v5
	v_fma_f32 v10, -v9, v5, v4
	v_cmp_ge_f32_e64 s[8:9], 0, v10
	v_add_u32_e32 v10, 1, v5
	s_add_i32 s45, s44, 4
	v_cndmask_b32_e64 v9, v5, v9, s[8:9]
	v_fma_f32 v5, -v10, v5, v4
	v_cmp_lt_f32_e64 s[8:9], 0, v5
	s_or_b32 s47, s44, 2
	s_or_b32 s48, s43, 31
	v_cndmask_b32_e64 v5, v9, v10, s[8:9]
	v_mul_f32_e32 v9, 0x37800000, v5
	v_cndmask_b32_e32 v5, v5, v9, vcc
	v_mov_b32_e32 v9, 0x260
	v_cmp_class_f32_e32 vcc, v4, v9
	s_add_i32 s52, s80, 0xff
	s_lshl_b32 s0, s0, 10
	v_cndmask_b32_e32 v4, v5, v4, vcc
	v_mul_f32_e32 v4, 0x3e38aa3b, v4
	v_mul_f32_e32 v5, 0x3f8147ae, v4
	v_min_f32_e32 v189, 0x42400000, v5
	v_fma_f32 v160, v11, s4, -v189
	s_mul_i32 s4, s42, 0x3fc
	s_add_i32 s49, s46, s4
	s_add_i32 s50, s49, s3
	s_sub_i32 s3, s80, 64
	v_fmamk_f32 v190, v4, 0x3f8147ae, v184
	v_add_u32_e32 v4, s3, v6
	v_ashrrev_i32_e32 v5, 31, v4
	v_lshlrev_b64 v[4:5], 11, v[4:5]
	v_lshl_add_u64 v[4:5], v[4:5], 0, s[10:11]
	s_add_i32 s3, s80, 0xffffff80
	v_lshl_add_u64 v[162:163], s[14:15], 0, v[4:5]
	v_lshl_add_u64 v[164:165], s[16:17], 0, v[4:5]
	v_add_u32_e32 v4, s3, v6
	s_add_u32 s1, s40, s1
	v_lshlrev_b32_e32 v10, 1, v2
	v_lshrrev_b32_e32 v12, 1, v2
	v_ashrrev_i32_e32 v5, 31, v4
	s_addc_u32 s3, s41, 0
	v_lshlrev_b32_e32 v156, 3, v7
	v_and_b32_e32 v9, 19, v2
	v_and_b32_e32 v10, 8, v10
	v_and_b32_e32 v12, 4, v12
	v_lshlrev_b32_e32 v187, 10, v7
	v_cmp_eq_u32_e64 s[8:9], 0, v6
	v_lshlrev_b64 v[4:5], 11, v[4:5]
	v_add_lshl_u32 v6, s80, v6, 11
	v_mov_b32_e32 v7, v1
	s_add_u32 s0, s1, s0
	v_mov_b32_e32 v80, v1
	v_mov_b32_e32 v81, v1
	v_mov_b32_e32 v140, v1
	v_mov_b32_e32 v141, v1
	v_or3_b32 v9, v10, v9, v12
	v_mul_u32_u24_e32 v185, 0x90, v8
	v_lshl_add_u64 v[4:5], v[4:5], 0, s[10:11]
	v_lshl_add_u64 v[6:7], v[6:7], 0, s[10:11]
	s_addc_u32 s1, s3, 0
	v_mov_b32_e32 v66, v1
	v_mov_b32_e32 v67, v1
	v_mov_b32_e32 v68, v1
	v_mov_b32_e32 v69, v1
	v_mov_b32_e32 v70, v1
	v_mov_b32_e32 v71, v1
	v_mov_b32_e32 v72, v1
	v_mov_b32_e32 v73, v1
	v_mov_b32_e32 v74, v1
	v_mov_b32_e32 v75, v1
	v_mov_b32_e32 v76, v1
	v_mov_b32_e32 v77, v1
	v_mov_b32_e32 v78, v1
	v_mov_b32_e32 v79, v1
	v_mov_b32_e32 v138, v1
	v_mov_b32_e32 v139, v1
	v_mov_b64_e32 v[148:149], v[140:141]
	v_mov_b64_e32 v[144:145], v[140:141]
	v_mov_b64_e32 v[152:153], v[140:141]
	v_mov_b64_e32 v[96:97], v[80:81]
	v_lshlrev_b64 v[158:159], 10, v[154:155]
	s_mov_b32 s2, 0
	s_mov_b32 s51, 8
	v_lshl_add_u32 v186, v9, 4, 0
	v_lshl_add_u32 v188, v156, 2, 0
	v_mov_b32_e32 v161, v160
	v_add3_u32 v191, 0, v185, v0
	v_lshl_add_u64 v[166:167], s[16:17], 0, v[4:5]
	v_lshl_add_u64 v[168:169], s[14:15], 0, v[6:7]
	v_lshl_add_u64 v[170:171], s[16:17], 0, v[6:7]
	v_lshl_add_u64 v[172:173], v[2:3], 2, s[0:1]
	v_lshl_add_u64 v[174:175], s[14:15], 0, v[4:5]
	v_mov_b32_e32 v193, 0xf149f2ca
	v_mov_b32_e32 v155, 0
	s_mov_b64 s[4:5], 0
	s_mov_b32 s53, 5
	v_mov_b64_e32 v[146:147], v[138:139]
	v_mov_b64_e32 v[142:143], v[138:139]
	v_mov_b64_e32 v[150:151], v[138:139]
	v_mov_b64_e32 v[94:95], v[78:79]
	v_mov_b64_e32 v[92:93], v[76:77]
	v_mov_b64_e32 v[90:91], v[74:75]
	v_mov_b64_e32 v[88:89], v[72:73]
	v_mov_b64_e32 v[86:87], v[70:71]
	v_mov_b64_e32 v[84:85], v[68:69]
	v_mov_b64_e32 v[82:83], v[66:67]
	s_waitcnt lgkmcnt(0)
	s_barrier
	s_branch .LBB0_964
